# attention: s_setprio 1 for waves 4-7 (static) on top of hand-scheduled S2
# baseline (speedup 1.0000x reference)
; __global__ __launch_bounds__(NTHREADS, 2) void hymba_mega(Params p) {
;     ...
;         for (int rep_ = 0; rep_ < (PROBE_REP == 4 ? 2 : 1); ++rep_)
;         for (int it = bid; it < 1024; it += G) {
;             const int xcd = it & 7, rest = it >> 3;
;             const int bh = xcd * 2 + (rest >> 6), j = rest & 63;
;             attn_unit(p, bh, 127 - j, lds, lam, tidA, laneA, wid, true);
;             attn_unit(p, bh, j, lds, lam, tidA, laneA, wid, false);
;         }
.Lccd_lo:
	s_mov_b32 s95, 0
	s_lshl_b32 s93, s60, 2
	s_cmp_lt_u32 s59, 64
	s_cbranch_scc1 .Lprio_skip
	s_setprio 1
.Lprio_skip:
	s_branch .LBB0_346
.LBB0_345:
	s_add_i32 s65, s65, s3
	s_add_i32 s62, s62, s63
	s_cmpk_gt_i32 s65, 0x3ff
	s_barrier
	s_cbranch_scc1 .LBB0_386

; __global__ __launch_bounds__(NTHREADS, 2) void hymba_mega(Params p) {
;     ...
;         }
;     }
;     grid.sync();
.LBB0_386:
	s_setprio 0
	s_barrier
	s_and_saveexec_b64 s[4:5], s[0:1]
	s_cbranch_execz .LBB0_396
	buffer_wbl2 sc1
	s_waitcnt vmcnt(0)
	s_load_dwordx2 s[6:7], s[48:49], 0x58
	v_mov_b32_e32 v2, 0
	s_mov_b64 s[8:9], exec
	v_mbcnt_lo_u32_b32 v1, s8, 0
	v_mbcnt_hi_u32_b32 v1, s9, v1
	s_waitcnt lgkmcnt(0)
	global_load_dword v0, v2, s[6:7] offset:40
	v_cmp_eq_u32_e32 vcc, 0, v1
	s_and_saveexec_b64 s[10:11], vcc
	s_cbranch_execz .LBB0_389
	s_bcnt1_i32_b64 s8, s[8:9]
	v_mov_b32_e32 v3, s8
	global_atomic_add v3, v2, v3, s[6:7] offset:32 sc0
